# stack4 + QK^T chain with two K-fragment LDS reads in flight (double-buffered)
# speedup vs baseline: 1.0229x; 1.0051x over previous
.Li0_entry:
	v_add_u32_e32 v167, s79, v147
	v_add_u32_e32 v192, s79, v149
	v_add_u32_e32 v193, s79, v151
	v_add_u32_e32 v194, s79, v153
	ds_read_b128 v[64:67], v167
	ds_read_b128 v[180:183], v192
	s_waitcnt lgkmcnt(2)
	v_max_f32_e32 v72, v166, v166
	v_max_f32_e32 v73, v164, v164
	v_max_f32_e32 v72, v73, v72
	v_sub_f32_e32 v73, v72, v165
	v_mul_f32_e32 v73, 0x3db504f3, v73
	v_cmp_ge_f32_e32 vcc, s88, v73
	s_cmp_eq_u64 vcc, exec
	s_cbranch_scc0 .Li0_orig
	ds_read_b128 v[188:191], v193
	s_waitcnt lgkmcnt(2)
	v_mfma_f32_32x32x16_bf16 v[64:79], v[64:67], v[80:83], 0
	s_waitcnt lgkmcnt(1)
	v_mfma_f32_32x32x16_bf16 v[64:79], v[180:183], v[84:87], v[64:79]
	ds_read_b128 v[180:183], v194
	s_mov_b64 s[54:55], 0xe404000
	s_add_i32 m0, s96, 0x8000
	v_lshl_add_u64 v[184:185], v[134:135], 0, s[54:55]
	s_nop 0
	global_load_lds_dwordx4 v[184:185], off
	v_cndmask_b32_e64 v173, v113, v121, s[2:3]
	v_cndmask_b32_e64 v172, v112, v120, s[2:3]
	v_cndmask_b32_e64 v177, v121, v113, s[2:3]
	v_cndmask_b32_e64 v176, v120, v112, s[2:3]
	s_waitcnt lgkmcnt(1)
	v_mfma_f32_32x32x16_bf16 v[64:79], v[188:191], v[88:91], v[64:79]
	ds_read_b128 v[188:191], v167 offset:128
	s_mov_b64 s[54:55], 0xe406000
	s_add_i32 m0, s96, 0xa000
	v_lshl_add_u64 v[184:185], v[134:135], 0, s[54:55]
	s_nop 0
	global_load_lds_dwordx4 v[184:185], off
	v_cndmask_b32_e64 v171, v119, v127, s[2:3]
	v_cndmask_b32_e64 v170, v118, v126, s[2:3]
	v_cndmask_b32_e64 v169, v117, v125, s[2:3]
	v_cndmask_b32_e64 v168, v116, v124, s[2:3]
	s_waitcnt lgkmcnt(1)
	v_mfma_f32_32x32x16_bf16 v[64:79], v[180:183], v[92:95], v[64:79]
	ds_read_b128 v[180:183], v192 offset:128
	s_mov_b64 s[54:55], 0xe804000
	s_add_i32 m0, s96, 0xc000
	v_lshl_add_u64 v[184:185], v[134:135], 0, s[54:55]
	s_nop 0
	global_load_lds_dwordx4 v[184:185], off
	v_cndmask_b32_e64 v175, v115, v123, s[2:3]
	v_cndmask_b32_e64 v174, v114, v122, s[2:3]
	v_cndmask_b32_e64 v127, v127, v119, s[2:3]
	v_cndmask_b32_e64 v126, v126, v118, s[2:3]
	s_waitcnt lgkmcnt(1)
	v_mfma_f32_32x32x16_bf16 v[64:79], v[188:191], v[96:99], v[64:79]
	ds_read_b128 v[188:191], v193 offset:128
	s_mov_b64 s[54:55], 0xe806000
	s_add_i32 m0, s96, 0xe000
	v_lshl_add_u64 v[184:185], v[134:135], 0, s[54:55]
	s_nop 0
	global_load_lds_dwordx4 v[184:185], off
	v_cndmask_b32_e64 v125, v125, v117, s[2:3]
	v_cndmask_b32_e64 v124, v124, v116, s[2:3]
	v_cndmask_b32_e64 v179, v123, v115, s[2:3]
	v_cndmask_b32_e64 v178, v122, v114, s[2:3]
	s_waitcnt lgkmcnt(1)
	v_mfma_f32_32x32x16_bf16 v[64:79], v[180:183], v[100:103], v[64:79]
	ds_read_b128 v[180:183], v194 offset:128
	s_cmp_gt_i32 s19, s18
	s_cbranch_scc1 .Li0_kskip
	v_lshl_add_u64 v[186:187], s[50:51], 0, v[130:131]
	s_mov_b64 s[54:55], 0xc408000
	s_mov_b32 m0, s97
	v_lshl_add_u64 v[184:185], v[186:187], 0, s[54:55]
	s_mov_b64 s[54:55], 0xc40a000
	global_load_lds_dwordx4 v[184:185], off
	s_mov_b32 m0, s26
	v_lshl_add_u64 v[186:187], v[186:187], 0, s[54:55]
	s_nop 0
	global_load_lds_dwordx4 v[186:187], off
.Li0_kskip:
	s_waitcnt lgkmcnt(1)
	v_mfma_f32_32x32x16_bf16 v[64:79], v[188:191], v[104:107], v[64:79]
	v_mov_b32_e32 v166, v165
	s_waitcnt lgkmcnt(0)
	v_mfma_f32_32x32x16_bf16 v[64:79], v[180:183], v[108:111], v[64:79]
	s_sub_i32 s52, s83, 64
	s_cmp_le_i32 s52, s25
	s_cbranch_scc1 .Li0_sm
	s_nop 7
	v_add_u32_e32 v112, 0x5b, v162
	v_cmp_gt_u32_e32 vcc, s86, v112
	v_add_u32_e32 v112, s83, v163
	v_add_u32_e32 v112, 0xffffffa1, v112
	v_cndmask_b32_e32 v64, v141, v64, vcc
	v_cmp_lt_u32_e32 vcc, s87, v112
	v_add_u32_e32 v112, 0x59, v162
	s_nop 0
	v_cndmask_b32_e32 v65, v141, v65, vcc
	v_cmp_gt_u32_e32 vcc, s86, v112
	v_add_u32_e32 v112, 0x58, v162
	s_nop 0
	v_cndmask_b32_e32 v66, v141, v66, vcc
	v_cmp_gt_u32_e32 vcc, s86, v112
	v_add_u32_e32 v112, 0x53, v162
	s_nop 0
	v_cndmask_b32_e32 v67, v141, v67, vcc
	v_cmp_gt_u32_e32 vcc, s86, v112
	v_add_u32_e32 v112, 0x52, v162
	s_nop 0
	v_cndmask_b32_e32 v68, v141, v68, vcc
	v_cmp_gt_u32_e32 vcc, s86, v112
	v_add_u32_e32 v112, 0x51, v162
	s_nop 0
	v_cndmask_b32_e32 v69, v141, v69, vcc
	v_cmp_gt_u32_e32 vcc, s86, v112
	v_add_u32_e32 v112, 0x50, v162
	s_nop 0
	v_cndmask_b32_e32 v70, v141, v70, vcc
	v_cmp_gt_u32_e32 vcc, s86, v112
	v_add_u32_e32 v112, 0x4b, v162
	s_nop 0
	v_cndmask_b32_e32 v71, v141, v71, vcc
	v_cmp_gt_u32_e32 vcc, s86, v112
	v_add_u32_e32 v112, 0x4a, v162
	s_nop 0
	v_cndmask_b32_e32 v72, v141, v72, vcc
	v_cmp_gt_u32_e32 vcc, s86, v112
	v_add_u32_e32 v112, 0x49, v162
	s_nop 0
	v_cndmask_b32_e32 v73, v141, v73, vcc
	v_cmp_gt_u32_e32 vcc, s86, v112
	v_add_u32_e32 v112, 0x48, v162
	s_nop 0
	v_cndmask_b32_e32 v74, v141, v74, vcc
	v_cmp_gt_u32_e32 vcc, s86, v112
	v_add_u32_e32 v112, 0x43, v162
	s_nop 0
	v_cndmask_b32_e32 v75, v141, v75, vcc
	v_cmp_gt_u32_e32 vcc, s86, v112
	v_add_u32_e32 v112, 0x42, v162
	s_nop 0
	v_cndmask_b32_e32 v76, v141, v76, vcc
	v_cmp_gt_u32_e32 vcc, s86, v112
	v_add_u32_e32 v112, 0x41, v162
	s_nop 0
	v_cndmask_b32_e32 v77, v141, v77, vcc
	v_cmp_gt_u32_e32 vcc, s86, v112
	v_add_u32_e32 v112, 64, v162
	s_nop 0
	v_cndmask_b32_e32 v78, v141, v78, vcc
	v_cmp_gt_u32_e32 vcc, s86, v112
	s_nop 1
	v_cndmask_b32_e32 v79, v141, v79, vcc

.Li1_entry:
	ds_read_b128 v[64:67], v148
	ds_read_b128 v[180:183], v150
	s_waitcnt lgkmcnt(2)
	v_max_f32_e32 v72, v128, v128
	v_max_f32_e32 v73, v164, v164
	v_max_f32_e32 v72, v73, v72
	v_sub_f32_e32 v73, v72, v166
	v_mul_f32_e32 v73, 0x3db504f3, v73
	v_cmp_ge_f32_e32 vcc, s88, v73
	s_cmp_eq_u64 vcc, exec
	s_cbranch_scc0 .Li1_orig
	ds_read_b128 v[188:191], v152
	s_waitcnt lgkmcnt(2)
	v_mfma_f32_32x32x16_bf16 v[64:79], v[64:67], v[80:83], 0
	s_waitcnt lgkmcnt(1)
	v_mfma_f32_32x32x16_bf16 v[64:79], v[180:183], v[84:87], v[64:79]
	ds_read_b128 v[180:183], v154
	s_mov_b64 s[56:57], 0xe408000
	s_mov_b32 m0, s96
	v_lshl_add_u64 v[184:185], v[134:135], 0, s[56:57]
	s_nop 0
	global_load_lds_dwordx4 v[184:185], off
	v_cndmask_b32_e64 v173, v113, v121, s[2:3]
	v_cndmask_b32_e64 v172, v112, v120, s[2:3]
	v_cndmask_b32_e64 v177, v121, v113, s[2:3]
	v_cndmask_b32_e64 v176, v120, v112, s[2:3]
	s_waitcnt lgkmcnt(1)
	v_mfma_f32_32x32x16_bf16 v[64:79], v[188:191], v[88:91], v[64:79]
	ds_read_b128 v[188:191], v148 offset:128
	s_mov_b64 s[56:57], 0xe40a000
	s_mov_b32 m0, s6
	v_lshl_add_u64 v[184:185], v[134:135], 0, s[56:57]
	s_nop 0
	global_load_lds_dwordx4 v[184:185], off
	v_cndmask_b32_e64 v171, v127, v119, s[2:3]
	v_cndmask_b32_e64 v170, v126, v118, s[2:3]
	v_cndmask_b32_e64 v169, v125, v117, s[2:3]
	v_cndmask_b32_e64 v168, v124, v116, s[2:3]
	s_waitcnt lgkmcnt(1)
	v_mfma_f32_32x32x16_bf16 v[64:79], v[180:183], v[92:95], v[64:79]
	ds_read_b128 v[180:183], v150 offset:128
	s_mov_b64 s[56:57], 0xe808000
	s_mov_b32 m0, s7
	v_lshl_add_u64 v[184:185], v[134:135], 0, s[56:57]
	s_nop 0
	global_load_lds_dwordx4 v[184:185], off
	v_cndmask_b32_e64 v175, v115, v123, s[2:3]
	v_cndmask_b32_e64 v174, v114, v122, s[2:3]
	v_cndmask_b32_e64 v127, v119, v127, s[2:3]
	v_cndmask_b32_e64 v126, v118, v126, s[2:3]
	s_waitcnt lgkmcnt(1)
	v_mfma_f32_32x32x16_bf16 v[64:79], v[188:191], v[96:99], v[64:79]
	ds_read_b128 v[188:191], v152 offset:128
	s_mov_b64 s[56:57], 0xe80a000
	s_mov_b32 m0, s24
	v_lshl_add_u64 v[184:185], v[134:135], 0, s[56:57]
	s_nop 0
	global_load_lds_dwordx4 v[184:185], off
	v_cndmask_b32_e64 v125, v117, v125, s[2:3]
	v_cndmask_b32_e64 v124, v116, v124, s[2:3]
	v_cndmask_b32_e64 v179, v123, v115, s[2:3]
	v_cndmask_b32_e64 v178, v122, v114, s[2:3]
	s_waitcnt lgkmcnt(1)
	v_mfma_f32_32x32x16_bf16 v[64:79], v[180:183], v[100:103], v[64:79]
	ds_read_b128 v[180:183], v154 offset:128
	s_add_i32 s56, s19, 1
	s_cmp_gt_i32 s56, s18
	s_cbranch_scc1 .Li1_kskip
	v_lshl_add_u64 v[186:187], s[50:51], 0, v[130:131]
	s_mov_b64 s[56:57], 0xc40c000
	s_mov_b32 m0, s27
	v_lshl_add_u64 v[184:185], v[186:187], 0, s[56:57]
	s_mov_b64 s[56:57], 0xc40e000
	global_load_lds_dwordx4 v[184:185], off
	s_mov_b32 m0, s62
	v_lshl_add_u64 v[186:187], v[186:187], 0, s[56:57]
	s_nop 0
	global_load_lds_dwordx4 v[186:187], off
.Li1_kskip:
	s_waitcnt lgkmcnt(1)
	v_mfma_f32_32x32x16_bf16 v[64:79], v[188:191], v[104:107], v[64:79]
	v_mov_b32_e32 v165, v166
	s_waitcnt lgkmcnt(0)
	v_mfma_f32_32x32x16_bf16 v[64:79], v[180:183], v[108:111], v[64:79]
	s_cmp_le_i32 s83, s25
	s_cbranch_scc1 .Li1_sm
	s_nop 7
	v_add_u32_e32 v112, 27, v162
	v_cmp_gt_u32_e32 vcc, s86, v112
	v_add_u32_e32 v112, s83, v163
	v_subrev_u32_e32 v112, 31, v112
	v_cndmask_b32_e32 v64, v141, v64, vcc
	v_cmp_lt_u32_e32 vcc, s87, v112
	v_add_u32_e32 v112, 25, v162
	s_nop 0
	v_cndmask_b32_e32 v65, v141, v65, vcc
	v_cmp_gt_u32_e32 vcc, s86, v112
	v_add_u32_e32 v112, 24, v162
	s_nop 0
	v_cndmask_b32_e32 v66, v141, v66, vcc
	v_cmp_gt_u32_e32 vcc, s86, v112
	v_add_u32_e32 v112, 19, v162
	s_nop 0
	v_cndmask_b32_e32 v67, v141, v67, vcc
	v_cmp_gt_u32_e32 vcc, s86, v112
	v_add_u32_e32 v112, 18, v162
	s_nop 0
	v_cndmask_b32_e32 v68, v141, v68, vcc
	v_cmp_gt_u32_e32 vcc, s86, v112
	v_add_u32_e32 v112, 17, v162
	s_nop 0
	v_cndmask_b32_e32 v69, v141, v69, vcc
	v_cmp_gt_u32_e32 vcc, s86, v112
	v_add_u32_e32 v112, 16, v162
	s_nop 0
	v_cndmask_b32_e32 v70, v141, v70, vcc
	v_cmp_gt_u32_e32 vcc, s86, v112
	v_add_u32_e32 v112, 11, v162
	s_nop 0
	v_cndmask_b32_e32 v71, v141, v71, vcc
	v_cmp_gt_u32_e32 vcc, s86, v112
	v_add_u32_e32 v112, 10, v162
	s_nop 0
	v_cndmask_b32_e32 v72, v141, v72, vcc
	v_cmp_gt_u32_e32 vcc, s86, v112
	v_add_u32_e32 v112, 9, v162
	s_nop 0
	v_cndmask_b32_e32 v73, v141, v73, vcc
	v_cmp_gt_u32_e32 vcc, s86, v112
	v_add_u32_e32 v112, 8, v162
	s_nop 0
	v_cndmask_b32_e32 v74, v141, v74, vcc
	v_cmp_gt_u32_e32 vcc, s86, v112
	v_add_u32_e32 v112, 3, v162
	s_nop 0
	v_cndmask_b32_e32 v75, v141, v75, vcc
	v_cmp_gt_u32_e32 vcc, s86, v112
	v_add_u32_e32 v112, 2, v162
	s_nop 0
	v_cndmask_b32_e32 v76, v141, v76, vcc
	v_cmp_gt_u32_e32 vcc, s86, v112
	v_add_u32_e32 v112, 1, v162
	s_nop 0
	v_cndmask_b32_e32 v77, v141, v77, vcc
	v_cmp_gt_u32_e32 vcc, s86, v112
	s_nop 1
	v_cndmask_b32_e32 v78, v141, v78, vcc
	v_cmp_gt_u32_e32 vcc, s86, v162
	s_nop 1
	v_cndmask_b32_e32 v79, v141, v79, vcc
